# split-phase P2->P3 seam: late-GEMM workgroups arrive, run their in-projection unit, then wait for the release and acquire before their first mixer task
# speedup vs baseline: 1.0122x; 1.0122x over previous
; __device__ __forceinline__ unsigned xb_ld(unsigned* p)              { return __hip_atomic_load(p, __ATOMIC_RELAXED, __HIP_MEMORY_SCOPE_AGENT); }
; __device__ __forceinline__ unsigned xb_add(unsigned* p, unsigned v) { return __hip_atomic_fetch_add(p, v, __ATOMIC_RELAXED, __HIP_MEMORY_SCOPE_AGENT); }
; #define XB_SPIN(cond, bar) do { unsigned _sp = 0; while (cond) { __builtin_amdgcn_s_sleep(1); \
;     if ((++_sp & 255u) == 0u) { if (xb_ld(&(bar)[XB_TMO])) break; if (_sp > XB_SPIN_CAP) { atomicAdd(&(bar)[XB_TMO], 1u); break; } } } } while (0)
; __device__ __forceinline__ void xcd_barrier(const XcdBarrier& b) {
;     ...
;         const unsigned old = xb_add(&bar[XB_XSUB(b.x)], 1u);
;         const unsigned gen = old / nloc;
;         if (old + 1u == (gen + 1u) * nloc) {
;             __builtin_amdgcn_fence(__ATOMIC_RELEASE, "agent");
;             asm volatile("s_waitcnt vmcnt(0)" ::: "memory");
;             const unsigned og = xb_add(&bar[XB_TOP], 1u);
;             const unsigned tg = og / nx;
;             if (og + 1u == (tg + 1u) * nx) xb_add(&bar[XB_TOPGEN], 1u);
;             else XB_SPIN(xb_ld(&bar[XB_TOPGEN]) == tg, bar);
;             __builtin_amdgcn_fence(__ATOMIC_ACQUIRE, "agent");
;             xb_add(&bar[XB_XGEN(b.x)], 1u);
;             asm volatile("s_waitcnt vmcnt(0)" ::: "memory");
;         } else {
;             XB_SPIN(xb_ld(&bar[XB_XGEN(b.x)]) == gen, bar);
.LBB0_302:
	s_or_b64 exec, exec, s[38:39]
	v_cvt_f32_u32_e32 v5, v3
	s_waitcnt vmcnt(0)
	v_readfirstlane_b32 s12, v4
	v_sub_u32_e32 v4, 0, v3
	v_rcp_iflag_f32_e32 v5, v5
	v_add_u32_e32 v6, s12, v0
	v_mul_f32_e32 v5, 0x4f7ffffe, v5
	v_cvt_u32_f32_e32 v5, v5
	v_mul_lo_u32 v0, v4, v5
	v_mul_hi_u32 v0, v5, v0
	v_add_u32_e32 v0, v5, v0
	v_mul_hi_u32 v0, v6, v0
	v_mul_lo_u32 v4, v0, v3
	v_sub_u32_e32 v4, v6, v4
	v_add_u32_e32 v5, 1, v0
	v_cmp_ge_u32_e32 vcc, v4, v3
	s_nop 1
	v_cndmask_b32_e32 v0, v0, v5, vcc
	v_sub_u32_e32 v5, v4, v3
	v_cndmask_b32_e32 v4, v4, v5, vcc
	v_add_u32_e32 v5, 1, v0
	v_cmp_ge_u32_e32 vcc, v4, v3
	v_add_u32_e32 v4, 1, v6
	s_nop 0
	v_cndmask_b32_e32 v0, v0, v5, vcc
	v_mul_lo_u32 v5, v3, v0
	v_add_u32_e32 v3, v5, v3
	v_cmp_ne_u32_e32 vcc, v4, v3
	s_mov_b32 s13, -1
	s_nop 0
	v_writelane_b32 v255, s13, 47
	s_and_saveexec_b64 s[12:13], vcc
	s_xor_b64 s[38:39], exec, s[12:13]
	s_cbranch_execz .LBB0_316
	buffer_inv sc1
	v_readlane_b32 s12, v255, 10
	v_readlane_b32 s13, v255, 11
	s_waitcnt lgkmcnt(0)
	s_nop 3
	global_load_dword v2, v1, s[12:13] sc1
	s_waitcnt vmcnt(0)
	v_cmp_eq_u32_e32 vcc, v2, v0
	v_readlane_b32 s26, v255, 31
	s_movk_i32 s27, 0x80
	s_cmp_lt_u32 s26, s27
	s_cbranch_scc0 .Lss_nodefer
	v_readfirstlane_b32 s27, v0
	s_nop 1
	v_writelane_b32 v255, s27, 47
	s_mov_b64 vcc, 0
.Lss_nodefer:
	s_and_saveexec_b64 s[40:41], vcc
	s_cbranch_execz .LBB0_315
	s_mov_b32 s12, 1
	s_mov_b64 s[42:43], 0
	s_branch .LBB0_306

; #define PG8_WAIT_V(n) asm volatile("s_waitcnt vmcnt(" #n ")" ::: "memory")
; #define PG8_BAR __builtin_amdgcn_s_barrier()
; __device__ __forceinline__ unsigned xb_ld(unsigned* p)              { return __hip_atomic_load(p, __ATOMIC_RELAXED, __HIP_MEMORY_SCOPE_AGENT); }
; #define XB_SPIN(cond, bar) do { unsigned _sp = 0; while (cond) { __builtin_amdgcn_s_sleep(1); \
;     if ((++_sp & 255u) == 0u) { if (xb_ld(&(bar)[XB_TMO])) break; if (_sp > XB_SPIN_CAP) { atomicAdd(&(bar)[XB_TMO], 1u); break; } } } } while (0)
; template <class Epi, class Sched, bool ALIGN_EPI>
; __device__ __forceinline__ void gemm_phase(PG8_LAS unsigned char* lds, const Gemm g, const Sched& S, const Epi& E) {
;     ...
;     PG8_WAIT_V(0);
;     if constexpr (!ALIGN_EPI) { if (wr == 0) PG8_BAR; }
;     PG8_BAR;
; __device__ __forceinline__ void xcd_barrier(const XcdBarrier& b) {
;     ...
;             XB_SPIN(xb_ld(&bar[XB_XGEN(b.x)]) == gen, bar);
;             __builtin_amdgcn_fence(__ATOMIC_ACQUIRE, "agent");
;             asm volatile("s_waitcnt vmcnt(0)" ::: "memory");
.LBB0_367:
	s_waitcnt vmcnt(0)
	v_readlane_b32 s70, v255, 31
	v_readlane_b32 s94, v255, 32
	v_readlane_b32 s67, v255, 34
	v_readlane_b32 s71, v255, 35
	s_movk_i32 s97, 0x2000
	s_movk_i32 s93, 0x6000
	s_mov_b32 s96, 0xa000
	s_barrier
	v_readlane_b32 s95, v255, 33
	v_readlane_b32 s12, v255, 10
	v_readlane_b32 s13, v255, 11
	v_readlane_b32 s9, v255, 47
	s_mov_b64 s[26:27], exec
	v_cmp_eq_u32_e32 vcc, 0, v147
	s_mov_b32 s6, 0
	s_nop 1
	s_and_b64 exec, exec, vcc
	s_cbranch_execz .Lss_done
.Lss_loop:
	global_load_dword v2, v1, s[12:13] sc1
	s_waitcnt vmcnt(0)
	v_readfirstlane_b32 s3, v2
	s_nop 0
	s_cmp_lg_u32 s3, s9
	s_cbranch_scc1 .Lss_ok
	s_sleep 1
	s_add_i32 s6, s6, 1
	s_cmpk_lt_u32 s6, 0x4000
	s_cbranch_scc1 .Lss_loop
.Lss_ok:
	buffer_inv sc1
	s_waitcnt vmcnt(0)
.Lss_done:
	s_mov_b64 exec, s[26:27]
	s_barrier
